# hand-written residual epilogue for bf16-base GEMMs: all loads of a column half before its stores
# baseline (speedup 1.0000x reference)
.LBB0_773:
	v_readlane_b32 s96, v254, 36
	v_readlane_b32 s97, v254, 37
	s_andn2_b64 vcc, exec, s[46:47]
	s_cbranch_vccnz .LBB0_806
	s_and_b64 vcc, exec, s[4:5]
	s_cbranch_vccnz .Lres_old_774
	s_ashr_i32 s7, s6, 31
	s_mov_b64 s[98:99], 0x8000
	s_mov_b64 s[100:101], 0x28000
	v_readlane_b32 s46, v254, 47
	v_readlane_b32 s47, v254, 48
	v_lshl_add_u64 v[184:185], v[188:189], 0, s[6:7]
	v_lshlrev_b64 v[248:249], 11, v[184:185]
	v_lshl_add_u64 v[248:249], v[172:173], 0, v[248:249]
	v_lshl_add_u64 v[186:187], v[184:185], 3, s[46:47]
	v_mov_b32_e32 v242, v248
	v_mov_b32_e32 v243, v249
	global_load_dwordx4 v[152:155], v[248:249], off
	global_load_dwordx2 v[214:215], v[186:187], off
	v_lshl_add_u64 v[248:249], v[248:249], 0, s[98:99]
	global_load_dwordx4 v[156:159], v[248:249], off
	global_load_dwordx2 v[216:217], v[186:187], off offset:128
	v_lshl_add_u64 v[248:249], v[248:249], 0, s[98:99]
	global_load_dwordx4 v[160:163], v[248:249], off
	global_load_dwordx2 v[218:219], v[186:187], off offset:256
	v_lshl_add_u64 v[248:249], v[248:249], 0, s[98:99]
	global_load_dwordx4 v[164:167], v[248:249], off
	global_load_dwordx2 v[220:221], v[186:187], off offset:384
	v_lshl_add_u64 v[248:249], v[248:249], 0, s[100:101]
	global_load_dwordx4 v[168:171], v[248:249], off
	global_load_dwordx2 v[222:223], v[186:187], off offset:1024
	v_lshl_add_u64 v[248:249], v[248:249], 0, s[98:99]
	global_load_dwordx4 v[172:175], v[248:249], off
	global_load_dwordx2 v[232:233], v[186:187], off offset:1152
	v_lshl_add_u64 v[248:249], v[248:249], 0, s[98:99]
	global_load_dwordx4 v[176:179], v[248:249], off
	global_load_dwordx2 v[234:235], v[186:187], off offset:1280
	v_lshl_add_u64 v[248:249], v[248:249], 0, s[98:99]
	global_load_dwordx4 v[180:183], v[248:249], off
	global_load_dwordx2 v[250:251], v[186:187], off offset:1408
	v_mov_b32_e32 v248, v242
	v_mov_b32_e32 v249, v243
	s_waitcnt vmcnt(0)
	v_lshlrev_b32_e32 v184, 16, v152
	v_and_b32_e32 v185, 0xffff0000, v152
	v_lshlrev_b32_e32 v186, 16, v153
	v_and_b32_e32 v187, 0xffff0000, v153
	v_lshlrev_b32_e32 v188, 16, v154
	v_and_b32_e32 v189, 0xffff0000, v154
	v_lshlrev_b32_e32 v190, 16, v155
	v_and_b32_e32 v191, 0xffff0000, v155
	v_sub_f32_e32 v184, v184, v214
	v_sub_f32_e32 v185, v185, v214
	v_sub_f32_e32 v186, v186, v214
	v_sub_f32_e32 v187, v187, v214
	v_sub_f32_e32 v188, v188, v214
	v_sub_f32_e32 v189, v189, v214
	v_sub_f32_e32 v190, v190, v214
	v_sub_f32_e32 v191, v191, v214
	v_mul_f32_e32 v184, v215, v184
	v_mul_f32_e32 v185, v215, v185
	v_mul_f32_e32 v186, v215, v186
	v_mul_f32_e32 v187, v215, v187
	v_mul_f32_e32 v188, v215, v188
	v_mul_f32_e32 v189, v215, v189
	v_mul_f32_e32 v190, v215, v190
	v_mul_f32_e32 v191, v215, v191
	v_pk_fma_f32 v[184:185], v[144:145], v[184:185], v[148:149]
	v_pk_fma_f32 v[186:187], v[146:147], v[186:187], v[150:151]
	v_pk_fma_f32 v[188:189], v[136:137], v[188:189], v[140:141]
	v_pk_fma_f32 v[190:191], v[138:139], v[190:191], v[142:143]
	v_mul_f32_e32 v184, 0x3fb504f3, v184
	v_mul_f32_e32 v185, 0x3fb504f3, v185
	v_mul_f32_e32 v186, 0x3fb504f3, v186
	v_mul_f32_e32 v187, 0x3fb504f3, v187
	v_mul_f32_e32 v188, 0x3fb504f3, v188
	v_mul_f32_e32 v189, 0x3fb504f3, v189
	v_mul_f32_e32 v190, 0x3fb504f3, v190
	v_mul_f32_e32 v191, 0x3fb504f3, v191
	v_pk_fma_f32 v[184:185], v[132:133], v[124:125], v[184:185]
	v_pk_fma_f32 v[186:187], v[134:135], v[126:127], v[186:187]
	v_pk_fma_f32 v[188:189], v[128:129], v[60:61], v[188:189]
	v_pk_fma_f32 v[190:191], v[130:131], v[62:63], v[190:191]
	v_cvt_pk_bf16_f32 v152, v184, v185
	v_cvt_pk_bf16_f32 v153, v186, v187
	v_cvt_pk_bf16_f32 v154, v188, v189
	v_cvt_pk_bf16_f32 v155, v190, v191
	global_load_dwordx4 v[124:127], v[248:249], off offset:256
	v_lshl_add_u64 v[248:249], v[248:249], 0, s[98:99]
	v_lshlrev_b32_e32 v184, 16, v156
	v_and_b32_e32 v185, 0xffff0000, v156
	v_lshlrev_b32_e32 v186, 16, v157
	v_and_b32_e32 v187, 0xffff0000, v157
	v_lshlrev_b32_e32 v188, 16, v158
	v_and_b32_e32 v189, 0xffff0000, v158
	v_lshlrev_b32_e32 v190, 16, v159
	v_and_b32_e32 v191, 0xffff0000, v159
	v_sub_f32_e32 v184, v184, v216
	v_sub_f32_e32 v185, v185, v216
	v_sub_f32_e32 v186, v186, v216
	v_sub_f32_e32 v187, v187, v216
	v_sub_f32_e32 v188, v188, v216
	v_sub_f32_e32 v189, v189, v216
	v_sub_f32_e32 v190, v190, v216
	v_sub_f32_e32 v191, v191, v216
	v_mul_f32_e32 v184, v217, v184
	v_mul_f32_e32 v185, v217, v185
	v_mul_f32_e32 v186, v217, v186
	v_mul_f32_e32 v187, v217, v187
	v_mul_f32_e32 v188, v217, v188
	v_mul_f32_e32 v189, v217, v189
	v_mul_f32_e32 v190, v217, v190
	v_mul_f32_e32 v191, v217, v191
	v_pk_fma_f32 v[184:185], v[144:145], v[184:185], v[148:149]
	v_pk_fma_f32 v[186:187], v[146:147], v[186:187], v[150:151]
	v_pk_fma_f32 v[188:189], v[136:137], v[188:189], v[140:141]
	v_pk_fma_f32 v[190:191], v[138:139], v[190:191], v[142:143]
	v_mul_f32_e32 v184, 0x3fb504f3, v184
	v_mul_f32_e32 v185, 0x3fb504f3, v185
	v_mul_f32_e32 v186, 0x3fb504f3, v186
	v_mul_f32_e32 v187, 0x3fb504f3, v187
	v_mul_f32_e32 v188, 0x3fb504f3, v188
	v_mul_f32_e32 v189, 0x3fb504f3, v189
	v_mul_f32_e32 v190, 0x3fb504f3, v190
	v_mul_f32_e32 v191, 0x3fb504f3, v191
	v_pk_fma_f32 v[184:185], v[132:133], v[116:117], v[184:185]
	v_pk_fma_f32 v[186:187], v[134:135], v[118:119], v[186:187]
	v_pk_fma_f32 v[188:189], v[128:129], v[52:53], v[188:189]
	v_pk_fma_f32 v[190:191], v[130:131], v[54:55], v[190:191]
	v_cvt_pk_bf16_f32 v156, v184, v185
	v_cvt_pk_bf16_f32 v157, v186, v187
	v_cvt_pk_bf16_f32 v158, v188, v189
	v_cvt_pk_bf16_f32 v159, v190, v191
	global_load_dwordx4 v[116:119], v[248:249], off offset:256
	v_lshl_add_u64 v[248:249], v[248:249], 0, s[98:99]
	v_lshlrev_b32_e32 v184, 16, v160
	v_and_b32_e32 v185, 0xffff0000, v160
	v_lshlrev_b32_e32 v186, 16, v161
	v_and_b32_e32 v187, 0xffff0000, v161
	v_lshlrev_b32_e32 v188, 16, v162
	v_and_b32_e32 v189, 0xffff0000, v162
	v_lshlrev_b32_e32 v190, 16, v163
	v_and_b32_e32 v191, 0xffff0000, v163
	v_sub_f32_e32 v184, v184, v218
	v_sub_f32_e32 v185, v185, v218
	v_sub_f32_e32 v186, v186, v218
	v_sub_f32_e32 v187, v187, v218
	v_sub_f32_e32 v188, v188, v218
	v_sub_f32_e32 v189, v189, v218
	v_sub_f32_e32 v190, v190, v218
	v_sub_f32_e32 v191, v191, v218
	v_mul_f32_e32 v184, v219, v184
	v_mul_f32_e32 v185, v219, v185
	v_mul_f32_e32 v186, v219, v186
	v_mul_f32_e32 v187, v219, v187
	v_mul_f32_e32 v188, v219, v188
	v_mul_f32_e32 v189, v219, v189
	v_mul_f32_e32 v190, v219, v190
	v_mul_f32_e32 v191, v219, v191
	v_pk_fma_f32 v[184:185], v[144:145], v[184:185], v[148:149]
	v_pk_fma_f32 v[186:187], v[146:147], v[186:187], v[150:151]
	v_pk_fma_f32 v[188:189], v[136:137], v[188:189], v[140:141]
	v_pk_fma_f32 v[190:191], v[138:139], v[190:191], v[142:143]
	v_mul_f32_e32 v184, 0x3fb504f3, v184
	v_mul_f32_e32 v185, 0x3fb504f3, v185
	v_mul_f32_e32 v186, 0x3fb504f3, v186
	v_mul_f32_e32 v187, 0x3fb504f3, v187
	v_mul_f32_e32 v188, 0x3fb504f3, v188
	v_mul_f32_e32 v189, 0x3fb504f3, v189
	v_mul_f32_e32 v190, 0x3fb504f3, v190
	v_mul_f32_e32 v191, 0x3fb504f3, v191
	v_pk_fma_f32 v[184:185], v[132:133], v[108:109], v[184:185]
	v_pk_fma_f32 v[186:187], v[134:135], v[110:111], v[186:187]
	v_pk_fma_f32 v[188:189], v[128:129], v[44:45], v[188:189]
	v_pk_fma_f32 v[190:191], v[130:131], v[46:47], v[190:191]
	v_cvt_pk_bf16_f32 v160, v184, v185
	v_cvt_pk_bf16_f32 v161, v186, v187
	v_cvt_pk_bf16_f32 v162, v188, v189
	v_cvt_pk_bf16_f32 v163, v190, v191
	global_load_dwordx4 v[108:111], v[248:249], off offset:256
	v_lshl_add_u64 v[248:249], v[248:249], 0, s[98:99]
	v_lshlrev_b32_e32 v184, 16, v164
	v_and_b32_e32 v185, 0xffff0000, v164
	v_lshlrev_b32_e32 v186, 16, v165
	v_and_b32_e32 v187, 0xffff0000, v165
	v_lshlrev_b32_e32 v188, 16, v166
	v_and_b32_e32 v189, 0xffff0000, v166
	v_lshlrev_b32_e32 v190, 16, v167
	v_and_b32_e32 v191, 0xffff0000, v167
	v_sub_f32_e32 v184, v184, v220
	v_sub_f32_e32 v185, v185, v220
	v_sub_f32_e32 v186, v186, v220
	v_sub_f32_e32 v187, v187, v220
	v_sub_f32_e32 v188, v188, v220
	v_sub_f32_e32 v189, v189, v220
	v_sub_f32_e32 v190, v190, v220
	v_sub_f32_e32 v191, v191, v220
	v_mul_f32_e32 v184, v221, v184
	v_mul_f32_e32 v185, v221, v185
	v_mul_f32_e32 v186, v221, v186
	v_mul_f32_e32 v187, v221, v187
	v_mul_f32_e32 v188, v221, v188
	v_mul_f32_e32 v189, v221, v189
	v_mul_f32_e32 v190, v221, v190
	v_mul_f32_e32 v191, v221, v191
	v_pk_fma_f32 v[184:185], v[144:145], v[184:185], v[148:149]
	v_pk_fma_f32 v[186:187], v[146:147], v[186:187], v[150:151]
	v_pk_fma_f32 v[188:189], v[136:137], v[188:189], v[140:141]
	v_pk_fma_f32 v[190:191], v[138:139], v[190:191], v[142:143]
	v_mul_f32_e32 v184, 0x3fb504f3, v184
	v_mul_f32_e32 v185, 0x3fb504f3, v185
	v_mul_f32_e32 v186, 0x3fb504f3, v186
	v_mul_f32_e32 v187, 0x3fb504f3, v187
	v_mul_f32_e32 v188, 0x3fb504f3, v188
	v_mul_f32_e32 v189, 0x3fb504f3, v189
	v_mul_f32_e32 v190, 0x3fb504f3, v190
	v_mul_f32_e32 v191, 0x3fb504f3, v191
	v_pk_fma_f32 v[184:185], v[132:133], v[100:101], v[184:185]
	v_pk_fma_f32 v[186:187], v[134:135], v[102:103], v[186:187]
	v_pk_fma_f32 v[188:189], v[128:129], v[36:37], v[188:189]
	v_pk_fma_f32 v[190:191], v[130:131], v[38:39], v[190:191]
	v_cvt_pk_bf16_f32 v164, v184, v185
	v_cvt_pk_bf16_f32 v165, v186, v187
	v_cvt_pk_bf16_f32 v166, v188, v189
	v_cvt_pk_bf16_f32 v167, v190, v191
	global_load_dwordx4 v[100:103], v[248:249], off offset:256
	v_lshl_add_u64 v[248:249], v[248:249], 0, s[100:101]
	v_lshlrev_b32_e32 v184, 16, v168
	v_and_b32_e32 v185, 0xffff0000, v168
	v_lshlrev_b32_e32 v186, 16, v169
	v_and_b32_e32 v187, 0xffff0000, v169
	v_lshlrev_b32_e32 v188, 16, v170
	v_and_b32_e32 v189, 0xffff0000, v170
	v_lshlrev_b32_e32 v190, 16, v171
	v_and_b32_e32 v191, 0xffff0000, v171
	v_sub_f32_e32 v184, v184, v222
	v_sub_f32_e32 v185, v185, v222
	v_sub_f32_e32 v186, v186, v222
	v_sub_f32_e32 v187, v187, v222
	v_sub_f32_e32 v188, v188, v222
	v_sub_f32_e32 v189, v189, v222
	v_sub_f32_e32 v190, v190, v222
	v_sub_f32_e32 v191, v191, v222
	v_mul_f32_e32 v184, v223, v184
	v_mul_f32_e32 v185, v223, v185
	v_mul_f32_e32 v186, v223, v186
	v_mul_f32_e32 v187, v223, v187
	v_mul_f32_e32 v188, v223, v188
	v_mul_f32_e32 v189, v223, v189
	v_mul_f32_e32 v190, v223, v190
	v_mul_f32_e32 v191, v223, v191
	v_pk_fma_f32 v[184:185], v[144:145], v[184:185], v[148:149]
	v_pk_fma_f32 v[186:187], v[146:147], v[186:187], v[150:151]
	v_pk_fma_f32 v[188:189], v[136:137], v[188:189], v[140:141]
	v_pk_fma_f32 v[190:191], v[138:139], v[190:191], v[142:143]
	v_mul_f32_e32 v184, 0x3fb504f3, v184
	v_mul_f32_e32 v185, 0x3fb504f3, v185
	v_mul_f32_e32 v186, 0x3fb504f3, v186
	v_mul_f32_e32 v187, 0x3fb504f3, v187
	v_mul_f32_e32 v188, 0x3fb504f3, v188
	v_mul_f32_e32 v189, 0x3fb504f3, v189
	v_mul_f32_e32 v190, 0x3fb504f3, v190
	v_mul_f32_e32 v191, 0x3fb504f3, v191
	v_pk_fma_f32 v[184:185], v[132:133], v[92:93], v[184:185]
	v_pk_fma_f32 v[186:187], v[134:135], v[94:95], v[186:187]
	v_pk_fma_f32 v[188:189], v[128:129], v[28:29], v[188:189]
	v_pk_fma_f32 v[190:191], v[130:131], v[30:31], v[190:191]
	v_cvt_pk_bf16_f32 v168, v184, v185
	v_cvt_pk_bf16_f32 v169, v186, v187
	v_cvt_pk_bf16_f32 v170, v188, v189
	v_cvt_pk_bf16_f32 v171, v190, v191
	global_load_dwordx4 v[92:95], v[248:249], off offset:256
	v_lshl_add_u64 v[248:249], v[248:249], 0, s[98:99]
	v_lshlrev_b32_e32 v184, 16, v172
	v_and_b32_e32 v185, 0xffff0000, v172
	v_lshlrev_b32_e32 v186, 16, v173
	v_and_b32_e32 v187, 0xffff0000, v173
	v_lshlrev_b32_e32 v188, 16, v174
	v_and_b32_e32 v189, 0xffff0000, v174
	v_lshlrev_b32_e32 v190, 16, v175
	v_and_b32_e32 v191, 0xffff0000, v175
	v_sub_f32_e32 v184, v184, v232
	v_sub_f32_e32 v185, v185, v232
	v_sub_f32_e32 v186, v186, v232
	v_sub_f32_e32 v187, v187, v232
	v_sub_f32_e32 v188, v188, v232
	v_sub_f32_e32 v189, v189, v232
	v_sub_f32_e32 v190, v190, v232
	v_sub_f32_e32 v191, v191, v232
	v_mul_f32_e32 v184, v233, v184
	v_mul_f32_e32 v185, v233, v185
	v_mul_f32_e32 v186, v233, v186
	v_mul_f32_e32 v187, v233, v187
	v_mul_f32_e32 v188, v233, v188
	v_mul_f32_e32 v189, v233, v189
	v_mul_f32_e32 v190, v233, v190
	v_mul_f32_e32 v191, v233, v191
	v_pk_fma_f32 v[184:185], v[144:145], v[184:185], v[148:149]
	v_pk_fma_f32 v[186:187], v[146:147], v[186:187], v[150:151]
	v_pk_fma_f32 v[188:189], v[136:137], v[188:189], v[140:141]
	v_pk_fma_f32 v[190:191], v[138:139], v[190:191], v[142:143]
	v_mul_f32_e32 v184, 0x3fb504f3, v184
	v_mul_f32_e32 v185, 0x3fb504f3, v185
	v_mul_f32_e32 v186, 0x3fb504f3, v186
	v_mul_f32_e32 v187, 0x3fb504f3, v187
	v_mul_f32_e32 v188, 0x3fb504f3, v188
	v_mul_f32_e32 v189, 0x3fb504f3, v189
	v_mul_f32_e32 v190, 0x3fb504f3, v190
	v_mul_f32_e32 v191, 0x3fb504f3, v191
	v_pk_fma_f32 v[184:185], v[132:133], v[84:85], v[184:185]
	v_pk_fma_f32 v[186:187], v[134:135], v[86:87], v[186:187]
	v_pk_fma_f32 v[188:189], v[128:129], v[20:21], v[188:189]
	v_pk_fma_f32 v[190:191], v[130:131], v[22:23], v[190:191]
	v_cvt_pk_bf16_f32 v172, v184, v185
	v_cvt_pk_bf16_f32 v173, v186, v187
	v_cvt_pk_bf16_f32 v174, v188, v189
	v_cvt_pk_bf16_f32 v175, v190, v191
	global_load_dwordx4 v[84:87], v[248:249], off offset:256
	v_lshl_add_u64 v[248:249], v[248:249], 0, s[98:99]
	v_lshlrev_b32_e32 v184, 16, v176
	v_and_b32_e32 v185, 0xffff0000, v176
	v_lshlrev_b32_e32 v186, 16, v177
	v_and_b32_e32 v187, 0xffff0000, v177
	v_lshlrev_b32_e32 v188, 16, v178
	v_and_b32_e32 v189, 0xffff0000, v178
	v_lshlrev_b32_e32 v190, 16, v179
	v_and_b32_e32 v191, 0xffff0000, v179
	v_sub_f32_e32 v184, v184, v234
	v_sub_f32_e32 v185, v185, v234
	v_sub_f32_e32 v186, v186, v234
	v_sub_f32_e32 v187, v187, v234
	v_sub_f32_e32 v188, v188, v234
	v_sub_f32_e32 v189, v189, v234
	v_sub_f32_e32 v190, v190, v234
	v_sub_f32_e32 v191, v191, v234
	v_mul_f32_e32 v184, v235, v184
	v_mul_f32_e32 v185, v235, v185
	v_mul_f32_e32 v186, v235, v186
	v_mul_f32_e32 v187, v235, v187
	v_mul_f32_e32 v188, v235, v188
	v_mul_f32_e32 v189, v235, v189
	v_mul_f32_e32 v190, v235, v190
	v_mul_f32_e32 v191, v235, v191
	v_pk_fma_f32 v[184:185], v[144:145], v[184:185], v[148:149]
	v_pk_fma_f32 v[186:187], v[146:147], v[186:187], v[150:151]
	v_pk_fma_f32 v[188:189], v[136:137], v[188:189], v[140:141]
	v_pk_fma_f32 v[190:191], v[138:139], v[190:191], v[142:143]
	v_mul_f32_e32 v184, 0x3fb504f3, v184
	v_mul_f32_e32 v185, 0x3fb504f3, v185
	v_mul_f32_e32 v186, 0x3fb504f3, v186
	v_mul_f32_e32 v187, 0x3fb504f3, v187
	v_mul_f32_e32 v188, 0x3fb504f3, v188
	v_mul_f32_e32 v189, 0x3fb504f3, v189
	v_mul_f32_e32 v190, 0x3fb504f3, v190
	v_mul_f32_e32 v191, 0x3fb504f3, v191
	v_pk_fma_f32 v[184:185], v[132:133], v[76:77], v[184:185]
	v_pk_fma_f32 v[186:187], v[134:135], v[78:79], v[186:187]
	v_pk_fma_f32 v[188:189], v[128:129], v[12:13], v[188:189]
	v_pk_fma_f32 v[190:191], v[130:131], v[14:15], v[190:191]
	v_cvt_pk_bf16_f32 v176, v184, v185
	v_cvt_pk_bf16_f32 v177, v186, v187
	v_cvt_pk_bf16_f32 v178, v188, v189
	v_cvt_pk_bf16_f32 v179, v190, v191
	global_load_dwordx4 v[76:79], v[248:249], off offset:256
	v_lshl_add_u64 v[248:249], v[248:249], 0, s[98:99]
	v_lshlrev_b32_e32 v184, 16, v180
	v_and_b32_e32 v185, 0xffff0000, v180
	v_lshlrev_b32_e32 v186, 16, v181
	v_and_b32_e32 v187, 0xffff0000, v181
	v_lshlrev_b32_e32 v188, 16, v182
	v_and_b32_e32 v189, 0xffff0000, v182
	v_lshlrev_b32_e32 v190, 16, v183
	v_and_b32_e32 v191, 0xffff0000, v183
	v_sub_f32_e32 v184, v184, v250
	v_sub_f32_e32 v185, v185, v250
	v_sub_f32_e32 v186, v186, v250
	v_sub_f32_e32 v187, v187, v250
	v_sub_f32_e32 v188, v188, v250
	v_sub_f32_e32 v189, v189, v250
	v_sub_f32_e32 v190, v190, v250
	v_sub_f32_e32 v191, v191, v250
	v_mul_f32_e32 v184, v251, v184
	v_mul_f32_e32 v185, v251, v185
	v_mul_f32_e32 v186, v251, v186
	v_mul_f32_e32 v187, v251, v187
	v_mul_f32_e32 v188, v251, v188
	v_mul_f32_e32 v189, v251, v189
	v_mul_f32_e32 v190, v251, v190
	v_mul_f32_e32 v191, v251, v191
	v_pk_fma_f32 v[184:185], v[144:145], v[184:185], v[148:149]
	v_pk_fma_f32 v[186:187], v[146:147], v[186:187], v[150:151]
	v_pk_fma_f32 v[188:189], v[136:137], v[188:189], v[140:141]
	v_pk_fma_f32 v[190:191], v[138:139], v[190:191], v[142:143]
	v_mul_f32_e32 v184, 0x3fb504f3, v184
	v_mul_f32_e32 v185, 0x3fb504f3, v185
	v_mul_f32_e32 v186, 0x3fb504f3, v186
	v_mul_f32_e32 v187, 0x3fb504f3, v187
	v_mul_f32_e32 v188, 0x3fb504f3, v188
	v_mul_f32_e32 v189, 0x3fb504f3, v189
	v_mul_f32_e32 v190, 0x3fb504f3, v190
	v_mul_f32_e32 v191, 0x3fb504f3, v191
	v_pk_fma_f32 v[184:185], v[132:133], v[68:69], v[184:185]
	v_pk_fma_f32 v[186:187], v[134:135], v[70:71], v[186:187]
	v_pk_fma_f32 v[188:189], v[128:129], v[4:5], v[188:189]
	v_pk_fma_f32 v[190:191], v[130:131], v[6:7], v[190:191]
	v_cvt_pk_bf16_f32 v180, v184, v185
	v_cvt_pk_bf16_f32 v181, v186, v187
	v_cvt_pk_bf16_f32 v182, v188, v189
	v_cvt_pk_bf16_f32 v183, v190, v191
	global_load_dwordx4 v[68:71], v[248:249], off offset:256
	global_load_dwordx4 v[128:131], v[210:211], off offset:528
	global_load_dwordx4 v[132:135], v[210:211], off offset:512
	global_load_dwordx4 v[136:139], v[212:213], off offset:528
	global_load_dwordx4 v[144:147], v[212:213], off offset:512
	global_load_dwordx4 v[140:143], v[208:209], off offset:528
	global_load_dwordx4 v[148:151], v[208:209], off offset:512
	v_mov_b32_e32 v248, v242
	v_mov_b32_e32 v249, v243
	global_store_dwordx4 v[248:249], v[152:155], off
	v_lshl_add_u64 v[248:249], v[248:249], 0, s[98:99]
	global_store_dwordx4 v[248:249], v[156:159], off
	v_lshl_add_u64 v[248:249], v[248:249], 0, s[98:99]
	global_store_dwordx4 v[248:249], v[160:163], off
	v_lshl_add_u64 v[248:249], v[248:249], 0, s[98:99]
	global_store_dwordx4 v[248:249], v[164:167], off
	v_lshl_add_u64 v[248:249], v[248:249], 0, s[100:101]
	global_store_dwordx4 v[248:249], v[168:171], off
	v_lshl_add_u64 v[248:249], v[248:249], 0, s[98:99]
	global_store_dwordx4 v[248:249], v[172:175], off
	v_lshl_add_u64 v[248:249], v[248:249], 0, s[98:99]
	global_store_dwordx4 v[248:249], v[176:179], off
	v_lshl_add_u64 v[248:249], v[248:249], 0, s[98:99]
	global_store_dwordx4 v[248:249], v[180:183], off
	s_waitcnt vmcnt(8)
	v_lshlrev_b32_e32 v184, 16, v124
	v_and_b32_e32 v185, 0xffff0000, v124
	v_lshlrev_b32_e32 v186, 16, v125
	v_and_b32_e32 v187, 0xffff0000, v125
	v_lshlrev_b32_e32 v188, 16, v126
	v_and_b32_e32 v189, 0xffff0000, v126
	v_lshlrev_b32_e32 v190, 16, v127
	v_and_b32_e32 v191, 0xffff0000, v127
	v_sub_f32_e32 v184, v184, v214
	v_sub_f32_e32 v185, v185, v214
	v_sub_f32_e32 v186, v186, v214
	v_sub_f32_e32 v187, v187, v214
	v_sub_f32_e32 v188, v188, v214
	v_sub_f32_e32 v189, v189, v214
	v_sub_f32_e32 v190, v190, v214
	v_sub_f32_e32 v191, v191, v214
	v_mul_f32_e32 v184, v215, v184
	v_mul_f32_e32 v185, v215, v185
	v_mul_f32_e32 v186, v215, v186
	v_mul_f32_e32 v187, v215, v187
	v_mul_f32_e32 v188, v215, v188
	v_mul_f32_e32 v189, v215, v189
	v_mul_f32_e32 v190, v215, v190
	v_mul_f32_e32 v191, v215, v191
	v_pk_fma_f32 v[184:185], v[144:145], v[184:185], v[148:149]
	v_pk_fma_f32 v[186:187], v[146:147], v[186:187], v[150:151]
	v_pk_fma_f32 v[188:189], v[136:137], v[188:189], v[140:141]
	v_pk_fma_f32 v[190:191], v[138:139], v[190:191], v[142:143]
	v_mul_f32_e32 v184, 0x3fb504f3, v184
	v_mul_f32_e32 v185, 0x3fb504f3, v185
	v_mul_f32_e32 v186, 0x3fb504f3, v186
	v_mul_f32_e32 v187, 0x3fb504f3, v187
	v_mul_f32_e32 v188, 0x3fb504f3, v188
	v_mul_f32_e32 v189, 0x3fb504f3, v189
	v_mul_f32_e32 v190, 0x3fb504f3, v190
	v_mul_f32_e32 v191, 0x3fb504f3, v191
	v_pk_fma_f32 v[184:185], v[132:133], v[120:121], v[184:185]
	v_pk_fma_f32 v[186:187], v[134:135], v[122:123], v[186:187]
	v_pk_fma_f32 v[188:189], v[128:129], v[56:57], v[188:189]
	v_pk_fma_f32 v[190:191], v[130:131], v[58:59], v[190:191]
	v_cvt_pk_bf16_f32 v124, v184, v185
	v_cvt_pk_bf16_f32 v125, v186, v187
	v_cvt_pk_bf16_f32 v126, v188, v189
	v_cvt_pk_bf16_f32 v127, v190, v191
	v_lshlrev_b32_e32 v184, 16, v116
	v_and_b32_e32 v185, 0xffff0000, v116
	v_lshlrev_b32_e32 v186, 16, v117
	v_and_b32_e32 v187, 0xffff0000, v117
	v_lshlrev_b32_e32 v188, 16, v118
	v_and_b32_e32 v189, 0xffff0000, v118
	v_lshlrev_b32_e32 v190, 16, v119
	v_and_b32_e32 v191, 0xffff0000, v119
	v_sub_f32_e32 v184, v184, v216
	v_sub_f32_e32 v185, v185, v216
	v_sub_f32_e32 v186, v186, v216
	v_sub_f32_e32 v187, v187, v216
	v_sub_f32_e32 v188, v188, v216
	v_sub_f32_e32 v189, v189, v216
	v_sub_f32_e32 v190, v190, v216
	v_sub_f32_e32 v191, v191, v216
	v_mul_f32_e32 v184, v217, v184
	v_mul_f32_e32 v185, v217, v185
	v_mul_f32_e32 v186, v217, v186
	v_mul_f32_e32 v187, v217, v187
	v_mul_f32_e32 v188, v217, v188
	v_mul_f32_e32 v189, v217, v189
	v_mul_f32_e32 v190, v217, v190
	v_mul_f32_e32 v191, v217, v191
	v_pk_fma_f32 v[184:185], v[144:145], v[184:185], v[148:149]
	v_pk_fma_f32 v[186:187], v[146:147], v[186:187], v[150:151]
	v_pk_fma_f32 v[188:189], v[136:137], v[188:189], v[140:141]
	v_pk_fma_f32 v[190:191], v[138:139], v[190:191], v[142:143]
	v_mul_f32_e32 v184, 0x3fb504f3, v184
	v_mul_f32_e32 v185, 0x3fb504f3, v185
	v_mul_f32_e32 v186, 0x3fb504f3, v186
	v_mul_f32_e32 v187, 0x3fb504f3, v187
	v_mul_f32_e32 v188, 0x3fb504f3, v188
	v_mul_f32_e32 v189, 0x3fb504f3, v189
	v_mul_f32_e32 v190, 0x3fb504f3, v190
	v_mul_f32_e32 v191, 0x3fb504f3, v191
	v_pk_fma_f32 v[184:185], v[132:133], v[112:113], v[184:185]
	v_pk_fma_f32 v[186:187], v[134:135], v[114:115], v[186:187]
	v_pk_fma_f32 v[188:189], v[128:129], v[48:49], v[188:189]
	v_pk_fma_f32 v[190:191], v[130:131], v[50:51], v[190:191]
	v_cvt_pk_bf16_f32 v116, v184, v185
	v_cvt_pk_bf16_f32 v117, v186, v187
	v_cvt_pk_bf16_f32 v118, v188, v189
	v_cvt_pk_bf16_f32 v119, v190, v191
	v_lshlrev_b32_e32 v184, 16, v108
	v_and_b32_e32 v185, 0xffff0000, v108
	v_lshlrev_b32_e32 v186, 16, v109
	v_and_b32_e32 v187, 0xffff0000, v109
	v_lshlrev_b32_e32 v188, 16, v110
	v_and_b32_e32 v189, 0xffff0000, v110
	v_lshlrev_b32_e32 v190, 16, v111
	v_and_b32_e32 v191, 0xffff0000, v111
	v_sub_f32_e32 v184, v184, v218
	v_sub_f32_e32 v185, v185, v218
	v_sub_f32_e32 v186, v186, v218
	v_sub_f32_e32 v187, v187, v218
	v_sub_f32_e32 v188, v188, v218
	v_sub_f32_e32 v189, v189, v218
	v_sub_f32_e32 v190, v190, v218
	v_sub_f32_e32 v191, v191, v218
	v_mul_f32_e32 v184, v219, v184
	v_mul_f32_e32 v185, v219, v185
	v_mul_f32_e32 v186, v219, v186
	v_mul_f32_e32 v187, v219, v187
	v_mul_f32_e32 v188, v219, v188
	v_mul_f32_e32 v189, v219, v189
	v_mul_f32_e32 v190, v219, v190
	v_mul_f32_e32 v191, v219, v191
	v_pk_fma_f32 v[184:185], v[144:145], v[184:185], v[148:149]
	v_pk_fma_f32 v[186:187], v[146:147], v[186:187], v[150:151]
	v_pk_fma_f32 v[188:189], v[136:137], v[188:189], v[140:141]
	v_pk_fma_f32 v[190:191], v[138:139], v[190:191], v[142:143]
	v_mul_f32_e32 v184, 0x3fb504f3, v184
	v_mul_f32_e32 v185, 0x3fb504f3, v185
	v_mul_f32_e32 v186, 0x3fb504f3, v186
	v_mul_f32_e32 v187, 0x3fb504f3, v187
	v_mul_f32_e32 v188, 0x3fb504f3, v188
	v_mul_f32_e32 v189, 0x3fb504f3, v189
	v_mul_f32_e32 v190, 0x3fb504f3, v190
	v_mul_f32_e32 v191, 0x3fb504f3, v191
	v_pk_fma_f32 v[184:185], v[132:133], v[104:105], v[184:185]
	v_pk_fma_f32 v[186:187], v[134:135], v[106:107], v[186:187]
	v_pk_fma_f32 v[188:189], v[128:129], v[40:41], v[188:189]
	v_pk_fma_f32 v[190:191], v[130:131], v[42:43], v[190:191]
	v_cvt_pk_bf16_f32 v108, v184, v185
	v_cvt_pk_bf16_f32 v109, v186, v187
	v_cvt_pk_bf16_f32 v110, v188, v189
	v_cvt_pk_bf16_f32 v111, v190, v191
	v_lshlrev_b32_e32 v184, 16, v100
	v_and_b32_e32 v185, 0xffff0000, v100
	v_lshlrev_b32_e32 v186, 16, v101
	v_and_b32_e32 v187, 0xffff0000, v101
	v_lshlrev_b32_e32 v188, 16, v102
	v_and_b32_e32 v189, 0xffff0000, v102
	v_lshlrev_b32_e32 v190, 16, v103
	v_and_b32_e32 v191, 0xffff0000, v103
	v_sub_f32_e32 v184, v184, v220
	v_sub_f32_e32 v185, v185, v220
	v_sub_f32_e32 v186, v186, v220
	v_sub_f32_e32 v187, v187, v220
	v_sub_f32_e32 v188, v188, v220
	v_sub_f32_e32 v189, v189, v220
	v_sub_f32_e32 v190, v190, v220
	v_sub_f32_e32 v191, v191, v220
	v_mul_f32_e32 v184, v221, v184
	v_mul_f32_e32 v185, v221, v185
	v_mul_f32_e32 v186, v221, v186
	v_mul_f32_e32 v187, v221, v187
	v_mul_f32_e32 v188, v221, v188
	v_mul_f32_e32 v189, v221, v189
	v_mul_f32_e32 v190, v221, v190
	v_mul_f32_e32 v191, v221, v191
	v_pk_fma_f32 v[184:185], v[144:145], v[184:185], v[148:149]
	v_pk_fma_f32 v[186:187], v[146:147], v[186:187], v[150:151]
	v_pk_fma_f32 v[188:189], v[136:137], v[188:189], v[140:141]
	v_pk_fma_f32 v[190:191], v[138:139], v[190:191], v[142:143]
	v_mul_f32_e32 v184, 0x3fb504f3, v184
	v_mul_f32_e32 v185, 0x3fb504f3, v185
	v_mul_f32_e32 v186, 0x3fb504f3, v186
	v_mul_f32_e32 v187, 0x3fb504f3, v187
	v_mul_f32_e32 v188, 0x3fb504f3, v188
	v_mul_f32_e32 v189, 0x3fb504f3, v189
	v_mul_f32_e32 v190, 0x3fb504f3, v190
	v_mul_f32_e32 v191, 0x3fb504f3, v191
	v_pk_fma_f32 v[184:185], v[132:133], v[96:97], v[184:185]
	v_pk_fma_f32 v[186:187], v[134:135], v[98:99], v[186:187]
	v_pk_fma_f32 v[188:189], v[128:129], v[32:33], v[188:189]
	v_pk_fma_f32 v[190:191], v[130:131], v[34:35], v[190:191]
	v_cvt_pk_bf16_f32 v100, v184, v185
	v_cvt_pk_bf16_f32 v101, v186, v187
	v_cvt_pk_bf16_f32 v102, v188, v189
	v_cvt_pk_bf16_f32 v103, v190, v191
	v_lshlrev_b32_e32 v184, 16, v92
	v_and_b32_e32 v185, 0xffff0000, v92
	v_lshlrev_b32_e32 v186, 16, v93
	v_and_b32_e32 v187, 0xffff0000, v93
	v_lshlrev_b32_e32 v188, 16, v94
	v_and_b32_e32 v189, 0xffff0000, v94
	v_lshlrev_b32_e32 v190, 16, v95
	v_and_b32_e32 v191, 0xffff0000, v95
	v_sub_f32_e32 v184, v184, v222
	v_sub_f32_e32 v185, v185, v222
	v_sub_f32_e32 v186, v186, v222
	v_sub_f32_e32 v187, v187, v222
	v_sub_f32_e32 v188, v188, v222
	v_sub_f32_e32 v189, v189, v222
	v_sub_f32_e32 v190, v190, v222
	v_sub_f32_e32 v191, v191, v222
	v_mul_f32_e32 v184, v223, v184
	v_mul_f32_e32 v185, v223, v185
	v_mul_f32_e32 v186, v223, v186
	v_mul_f32_e32 v187, v223, v187
	v_mul_f32_e32 v188, v223, v188
	v_mul_f32_e32 v189, v223, v189
	v_mul_f32_e32 v190, v223, v190
	v_mul_f32_e32 v191, v223, v191
	v_pk_fma_f32 v[184:185], v[144:145], v[184:185], v[148:149]
	v_pk_fma_f32 v[186:187], v[146:147], v[186:187], v[150:151]
	v_pk_fma_f32 v[188:189], v[136:137], v[188:189], v[140:141]
	v_pk_fma_f32 v[190:191], v[138:139], v[190:191], v[142:143]
	v_mul_f32_e32 v184, 0x3fb504f3, v184
	v_mul_f32_e32 v185, 0x3fb504f3, v185
	v_mul_f32_e32 v186, 0x3fb504f3, v186
	v_mul_f32_e32 v187, 0x3fb504f3, v187
	v_mul_f32_e32 v188, 0x3fb504f3, v188
	v_mul_f32_e32 v189, 0x3fb504f3, v189
	v_mul_f32_e32 v190, 0x3fb504f3, v190
	v_mul_f32_e32 v191, 0x3fb504f3, v191
	v_pk_fma_f32 v[184:185], v[132:133], v[88:89], v[184:185]
	v_pk_fma_f32 v[186:187], v[134:135], v[90:91], v[186:187]
	v_pk_fma_f32 v[188:189], v[128:129], v[24:25], v[188:189]
	v_pk_fma_f32 v[190:191], v[130:131], v[26:27], v[190:191]
	v_cvt_pk_bf16_f32 v92, v184, v185
	v_cvt_pk_bf16_f32 v93, v186, v187
	v_cvt_pk_bf16_f32 v94, v188, v189
	v_cvt_pk_bf16_f32 v95, v190, v191
	v_lshlrev_b32_e32 v184, 16, v84
	v_and_b32_e32 v185, 0xffff0000, v84
	v_lshlrev_b32_e32 v186, 16, v85
	v_and_b32_e32 v187, 0xffff0000, v85
	v_lshlrev_b32_e32 v188, 16, v86
	v_and_b32_e32 v189, 0xffff0000, v86
	v_lshlrev_b32_e32 v190, 16, v87
	v_and_b32_e32 v191, 0xffff0000, v87
	v_sub_f32_e32 v184, v184, v232
	v_sub_f32_e32 v185, v185, v232
	v_sub_f32_e32 v186, v186, v232
	v_sub_f32_e32 v187, v187, v232
	v_sub_f32_e32 v188, v188, v232
	v_sub_f32_e32 v189, v189, v232
	v_sub_f32_e32 v190, v190, v232
	v_sub_f32_e32 v191, v191, v232
	v_mul_f32_e32 v184, v233, v184
	v_mul_f32_e32 v185, v233, v185
	v_mul_f32_e32 v186, v233, v186
	v_mul_f32_e32 v187, v233, v187
	v_mul_f32_e32 v188, v233, v188
	v_mul_f32_e32 v189, v233, v189
	v_mul_f32_e32 v190, v233, v190
	v_mul_f32_e32 v191, v233, v191
	v_pk_fma_f32 v[184:185], v[144:145], v[184:185], v[148:149]
	v_pk_fma_f32 v[186:187], v[146:147], v[186:187], v[150:151]
	v_pk_fma_f32 v[188:189], v[136:137], v[188:189], v[140:141]
	v_pk_fma_f32 v[190:191], v[138:139], v[190:191], v[142:143]
	v_mul_f32_e32 v184, 0x3fb504f3, v184
	v_mul_f32_e32 v185, 0x3fb504f3, v185
	v_mul_f32_e32 v186, 0x3fb504f3, v186
	v_mul_f32_e32 v187, 0x3fb504f3, v187
	v_mul_f32_e32 v188, 0x3fb504f3, v188
	v_mul_f32_e32 v189, 0x3fb504f3, v189
	v_mul_f32_e32 v190, 0x3fb504f3, v190
	v_mul_f32_e32 v191, 0x3fb504f3, v191
	v_pk_fma_f32 v[184:185], v[132:133], v[80:81], v[184:185]
	v_pk_fma_f32 v[186:187], v[134:135], v[82:83], v[186:187]
	v_pk_fma_f32 v[188:189], v[128:129], v[16:17], v[188:189]
	v_pk_fma_f32 v[190:191], v[130:131], v[18:19], v[190:191]
	v_cvt_pk_bf16_f32 v84, v184, v185
	v_cvt_pk_bf16_f32 v85, v186, v187
	v_cvt_pk_bf16_f32 v86, v188, v189
	v_cvt_pk_bf16_f32 v87, v190, v191
	v_lshlrev_b32_e32 v184, 16, v76
	v_and_b32_e32 v185, 0xffff0000, v76
	v_lshlrev_b32_e32 v186, 16, v77
	v_and_b32_e32 v187, 0xffff0000, v77
	v_lshlrev_b32_e32 v188, 16, v78
	v_and_b32_e32 v189, 0xffff0000, v78
	v_lshlrev_b32_e32 v190, 16, v79
	v_and_b32_e32 v191, 0xffff0000, v79
	v_sub_f32_e32 v184, v184, v234
	v_sub_f32_e32 v185, v185, v234
	v_sub_f32_e32 v186, v186, v234
	v_sub_f32_e32 v187, v187, v234
	v_sub_f32_e32 v188, v188, v234
	v_sub_f32_e32 v189, v189, v234
	v_sub_f32_e32 v190, v190, v234
	v_sub_f32_e32 v191, v191, v234
	v_mul_f32_e32 v184, v235, v184
	v_mul_f32_e32 v185, v235, v185
	v_mul_f32_e32 v186, v235, v186
	v_mul_f32_e32 v187, v235, v187
	v_mul_f32_e32 v188, v235, v188
	v_mul_f32_e32 v189, v235, v189
	v_mul_f32_e32 v190, v235, v190
	v_mul_f32_e32 v191, v235, v191
	v_pk_fma_f32 v[184:185], v[144:145], v[184:185], v[148:149]
	v_pk_fma_f32 v[186:187], v[146:147], v[186:187], v[150:151]
	v_pk_fma_f32 v[188:189], v[136:137], v[188:189], v[140:141]
	v_pk_fma_f32 v[190:191], v[138:139], v[190:191], v[142:143]
	v_mul_f32_e32 v184, 0x3fb504f3, v184
	v_mul_f32_e32 v185, 0x3fb504f3, v185
	v_mul_f32_e32 v186, 0x3fb504f3, v186
	v_mul_f32_e32 v187, 0x3fb504f3, v187
	v_mul_f32_e32 v188, 0x3fb504f3, v188
	v_mul_f32_e32 v189, 0x3fb504f3, v189
	v_mul_f32_e32 v190, 0x3fb504f3, v190
	v_mul_f32_e32 v191, 0x3fb504f3, v191
	v_pk_fma_f32 v[184:185], v[132:133], v[72:73], v[184:185]
	v_pk_fma_f32 v[186:187], v[134:135], v[74:75], v[186:187]
	v_pk_fma_f32 v[188:189], v[128:129], v[8:9], v[188:189]
	v_pk_fma_f32 v[190:191], v[130:131], v[10:11], v[190:191]
	v_cvt_pk_bf16_f32 v76, v184, v185
	v_cvt_pk_bf16_f32 v77, v186, v187
	v_cvt_pk_bf16_f32 v78, v188, v189
	v_cvt_pk_bf16_f32 v79, v190, v191
	v_lshlrev_b32_e32 v184, 16, v68
	v_and_b32_e32 v185, 0xffff0000, v68
	v_lshlrev_b32_e32 v186, 16, v69
	v_and_b32_e32 v187, 0xffff0000, v69
	v_lshlrev_b32_e32 v188, 16, v70
	v_and_b32_e32 v189, 0xffff0000, v70
	v_lshlrev_b32_e32 v190, 16, v71
	v_and_b32_e32 v191, 0xffff0000, v71
	v_sub_f32_e32 v184, v184, v250
	v_sub_f32_e32 v185, v185, v250
	v_sub_f32_e32 v186, v186, v250
	v_sub_f32_e32 v187, v187, v250
	v_sub_f32_e32 v188, v188, v250
	v_sub_f32_e32 v189, v189, v250
	v_sub_f32_e32 v190, v190, v250
	v_sub_f32_e32 v191, v191, v250
	v_mul_f32_e32 v184, v251, v184
	v_mul_f32_e32 v185, v251, v185
	v_mul_f32_e32 v186, v251, v186
	v_mul_f32_e32 v187, v251, v187
	v_mul_f32_e32 v188, v251, v188
	v_mul_f32_e32 v189, v251, v189
	v_mul_f32_e32 v190, v251, v190
	v_mul_f32_e32 v191, v251, v191
	v_pk_fma_f32 v[184:185], v[144:145], v[184:185], v[148:149]
	v_pk_fma_f32 v[186:187], v[146:147], v[186:187], v[150:151]
	v_pk_fma_f32 v[188:189], v[136:137], v[188:189], v[140:141]
	v_pk_fma_f32 v[190:191], v[138:139], v[190:191], v[142:143]
	v_mul_f32_e32 v184, 0x3fb504f3, v184
	v_mul_f32_e32 v185, 0x3fb504f3, v185
	v_mul_f32_e32 v186, 0x3fb504f3, v186
	v_mul_f32_e32 v187, 0x3fb504f3, v187
	v_mul_f32_e32 v188, 0x3fb504f3, v188
	v_mul_f32_e32 v189, 0x3fb504f3, v189
	v_mul_f32_e32 v190, 0x3fb504f3, v190
	v_mul_f32_e32 v191, 0x3fb504f3, v191
	v_pk_fma_f32 v[184:185], v[132:133], v[64:65], v[184:185]
	v_pk_fma_f32 v[186:187], v[134:135], v[66:67], v[186:187]
	v_pk_fma_f32 v[188:189], v[128:129], v[0:1], v[188:189]
	v_pk_fma_f32 v[190:191], v[130:131], v[2:3], v[190:191]
	v_cvt_pk_bf16_f32 v68, v184, v185
	v_cvt_pk_bf16_f32 v69, v186, v187
	v_cvt_pk_bf16_f32 v70, v188, v189
	v_cvt_pk_bf16_f32 v71, v190, v191
	v_mov_b32_e32 v248, v242
	v_mov_b32_e32 v249, v243
	global_store_dwordx4 v[248:249], v[124:127], off offset:256
	v_lshl_add_u64 v[248:249], v[248:249], 0, s[98:99]
	global_store_dwordx4 v[248:249], v[116:119], off offset:256
	v_lshl_add_u64 v[248:249], v[248:249], 0, s[98:99]
	global_store_dwordx4 v[248:249], v[108:111], off offset:256
	v_lshl_add_u64 v[248:249], v[248:249], 0, s[98:99]
	global_store_dwordx4 v[248:249], v[100:103], off offset:256
	v_lshl_add_u64 v[248:249], v[248:249], 0, s[100:101]
	global_store_dwordx4 v[248:249], v[92:95], off offset:256
	v_lshl_add_u64 v[248:249], v[248:249], 0, s[98:99]
	global_store_dwordx4 v[248:249], v[84:87], off offset:256
	v_lshl_add_u64 v[248:249], v[248:249], 0, s[98:99]
	global_store_dwordx4 v[248:249], v[76:79], off offset:256
	v_lshl_add_u64 v[248:249], v[248:249], 0, s[98:99]
	global_store_dwordx4 v[248:249], v[68:71], off offset:256
	s_mov_b64 s[4:5], 0
	s_branch .LBB0_844
.Lres_old_774:
	s_ashr_i32 s7, s6, 31
	v_lshl_add_u64 v[168:169], v[188:189], 0, s[6:7]
	v_lshlrev_b64 v[152:153], 11, v[168:169]
	v_lshl_add_u64 v[152:153], v[172:173], 0, v[152:153]
	global_load_dwordx4 v[164:167], v[152:153], off
	v_mov_b32_e32 v217, 1.0
	v_mov_b32_e32 v216, 0
	s_and_b64 vcc, exec, s[4:5]
	v_mov_b32_e32 v218, 0
	v_mov_b32_e32 v219, 1.0
	s_cbranch_vccnz .LBB0_776
	v_readlane_b32 s46, v254, 47
	v_readlane_b32 s47, v254, 48
	s_nop 1
	v_lshl_add_u64 v[152:153], v[168:169], 3, s[46:47]
	global_load_dwordx2 v[218:219], v[152:153], off
